# hyena units: MFMA loops software-pipelined over two LDS operand register sets; latent prologue loads issued together
# speedup vs baseline: 1.0123x; 1.0123x over previous
.LBB0_1247:
	s_or_b64 exec, exec, s[6:7]
	s_sub_i32 s8, s10, 32
	s_ashr_i32 s9, s8, 31
	s_lshl_b64 s[6:7], s[8:9], 12
	v_readlane_b32 s20, v252, 15
	v_readlane_b32 s21, v252, 16
	s_add_u32 s16, s20, s6
	s_addc_u32 s17, s21, s7
	s_add_u32 s18, s16, 0x100000
	s_addc_u32 s19, s17, 0
	s_mul_i32 s7, s8, 0x6000
	s_mul_hi_i32 s6, s8, 0x6000
	s_add_u32 s8, s42, s7
	s_addc_u32 s9, s43, s6
	s_add_u32 s12, s8, 0xd1f4000
	s_addc_u32 s13, s9, 0
	s_movk_i32 s11, 0x7ff
	s_movk_i32 s20, 0x800
	v_sub_u32_e32 v10, 0x81f, v8
	v_add_u32_e32 v11, -1, v10
	v_add_u32_e32 v12, 0xfffffe00, v10
	v_add_u32_e32 v13, -1, v12
	v_add_u32_e32 v14, 0xfffffe00, v12
	v_add_u32_e32 v15, -1, v14
	v_add_u32_e32 v16, 0xfffffe00, v14
	v_add_u32_e32 v17, -1, v16
	v_add_u32_e32 v18, 0xfffffe00, v16
	v_add_u32_e32 v19, -1, v18
	v_med3_i32 v20, v10, 0, s11
	v_med3_i32 v21, v11, 0, s11
	v_med3_i32 v22, v12, 0, s11
	v_med3_i32 v23, v13, 0, s11
	v_med3_i32 v24, v14, 0, s11
	v_med3_i32 v25, v15, 0, s11
	v_med3_i32 v26, v16, 0, s11
	v_med3_i32 v27, v17, 0, s11
	v_med3_i32 v28, v18, 0, s11
	v_med3_i32 v29, v19, 0, s11
	v_lshlrev_b32_e32 v20, 1, v20
	v_lshlrev_b32_e32 v21, 1, v21
	v_lshlrev_b32_e32 v22, 1, v22
	v_lshlrev_b32_e32 v23, 1, v23
	v_lshlrev_b32_e32 v24, 1, v24
	v_lshlrev_b32_e32 v25, 1, v25
	v_lshlrev_b32_e32 v26, 1, v26
	v_lshlrev_b32_e32 v27, 1, v27
	v_lshlrev_b32_e32 v28, 1, v28
	v_lshlrev_b32_e32 v29, 1, v29
	global_load_ushort v30, v20, s[16:17]
	global_load_ushort v31, v21, s[16:17]
	global_load_ushort v32, v20, s[18:19]
	global_load_ushort v33, v21, s[18:19]
	global_load_ushort v34, v22, s[16:17]
	global_load_ushort v35, v23, s[16:17]
	global_load_ushort v36, v22, s[18:19]
	global_load_ushort v37, v23, s[18:19]
	global_load_ushort v38, v24, s[16:17]
	global_load_ushort v39, v25, s[16:17]
	global_load_ushort v40, v24, s[18:19]
	global_load_ushort v41, v25, s[18:19]
	global_load_ushort v42, v26, s[16:17]
	global_load_ushort v43, v27, s[16:17]
	global_load_ushort v44, v26, s[18:19]
	global_load_ushort v45, v27, s[18:19]
	global_load_ushort v46, v28, s[16:17]
	global_load_ushort v47, v29, s[16:17]
	global_load_ushort v48, v28, s[18:19]
	global_load_ushort v49, v29, s[18:19]
	v_lshrrev_b32_e32 v4, 8, v8
	v_and_b32_e32 v5, 0xff, v8
	v_lshlrev_b32_e32 v6, 12, v4
	v_lshl_add_u32 v6, v5, 4, v6
	v_add_u32_e32 v7, 0x2000, v6
	global_load_dwordx4 v[70:73], v6, s[12:13]
	global_load_dwordx4 v[74:77], v7, s[12:13]
	v_lshl_add_u32 v50, v8, 4, v180
	v_lshl_add_u32 v50, v4, 10, v50
	v_lshlrev_b32_e32 v51, 1, v8
	s_waitcnt vmcnt(2)
	v_cmp_gt_u32_e32 vcc, 0x800, v10
	v_cmp_gt_u32_e64 s[6:7], s20, v11
	s_nop 1
	v_cndmask_b32_e32 v30, 0, v30, vcc
	v_cndmask_b32_e32 v32, 0, v32, vcc
	v_cndmask_b32_e64 v31, 0, v31, s[6:7]
	v_cndmask_b32_e64 v33, 0, v33, s[6:7]
	ds_write_b16 v51, v30
	ds_write_b16 v51, v31 offset:4192
	ds_write_b16 v51, v32 offset:8384
	ds_write_b16 v51, v33 offset:12576
	v_cmp_gt_u32_e32 vcc, 0x800, v12
	v_cmp_gt_u32_e64 s[6:7], s20, v13
	s_nop 1
	v_cndmask_b32_e32 v34, 0, v34, vcc
	v_cndmask_b32_e32 v36, 0, v36, vcc
	v_cndmask_b32_e64 v35, 0, v35, s[6:7]
	v_cndmask_b32_e64 v37, 0, v37, s[6:7]
	ds_write_b16 v51, v34 offset:1024
	ds_write_b16 v51, v35 offset:5216
	ds_write_b16 v51, v36 offset:9408
	ds_write_b16 v51, v37 offset:13600
	v_cmp_gt_u32_e32 vcc, 0x800, v14
	v_cmp_gt_u32_e64 s[6:7], s20, v15
	s_nop 1
	v_cndmask_b32_e32 v38, 0, v38, vcc
	v_cndmask_b32_e32 v40, 0, v40, vcc
	v_cndmask_b32_e64 v39, 0, v39, s[6:7]
	v_cndmask_b32_e64 v41, 0, v41, s[6:7]
	ds_write_b16 v51, v38 offset:2048
	ds_write_b16 v51, v39 offset:6240
	ds_write_b16 v51, v40 offset:10432
	ds_write_b16 v51, v41 offset:14624
	v_cmp_gt_u32_e32 vcc, 0x800, v16
	v_cmp_gt_u32_e64 s[6:7], s20, v17
	s_nop 1
	v_cndmask_b32_e32 v42, 0, v42, vcc
	v_cndmask_b32_e32 v44, 0, v44, vcc
	v_cndmask_b32_e64 v43, 0, v43, s[6:7]
	v_cndmask_b32_e64 v45, 0, v45, s[6:7]
	ds_write_b16 v51, v42 offset:3072
	ds_write_b16 v51, v43 offset:7264
	ds_write_b16 v51, v44 offset:11456
	ds_write_b16 v51, v45 offset:15648
	v_cmp_gt_u32_e32 vcc, 48, v8
	s_and_saveexec_b64 s[22:23], vcc
	v_cmp_gt_u32_e32 vcc, 0x800, v18
	v_cmp_gt_u32_e64 s[6:7], s20, v19
	s_nop 1
	v_cndmask_b32_e32 v46, 0, v46, vcc
	v_cndmask_b32_e32 v48, 0, v48, vcc
	v_cndmask_b32_e64 v47, 0, v47, s[6:7]
	v_cndmask_b32_e64 v49, 0, v49, s[6:7]
	ds_write_b16 v51, v46 offset:4096
	ds_write_b16 v51, v47 offset:8288
	ds_write_b16 v51, v48 offset:12480
	ds_write_b16 v51, v49 offset:16672
	s_or_b64 exec, exec, s[22:23]
	s_waitcnt lgkmcnt(0)
	s_barrier
	s_waitcnt vmcnt(0)
	ds_write_b128 v50, v[70:73]
	ds_write_b128 v50, v[74:77] offset:10240
	s_mov_b64 s[6:7], exec

.LBB0_1265:
	ds_read2_b32 v[92:93], v30 offset1:1
	ds_read2_b32 v[94:95], v30 offset0:2 offset1:3
	ds_read_b128 v[96:99], v31
	ds_read_b128 v[100:103], v31 offset:5120
	ds_read_b128 v[104:107], v31 offset:10240
	ds_read_b128 v[108:111], v31 offset:15360
	v_subrev_u32_e32 v30, 64, v30
	v_subrev_u32_e32 v31, 64, v31
	s_add_i32 s12, s12, 2
.Lhy_lat0_a:
	s_cmp_gt_i32 s12, s19
	s_cbranch_scc1 .Lhy_lat0_last_a
	ds_read2_b32 v[112:113], v30 offset1:1
	ds_read2_b32 v[114:115], v30 offset0:2 offset1:3
	ds_read_b128 v[116:119], v31
	ds_read_b128 v[120:123], v31 offset:5120
	ds_read_b128 v[124:127], v31 offset:10240
	ds_read_b128 v[132:135], v31 offset:15360
	v_subrev_u32_e32 v30, 64, v30
	v_subrev_u32_e32 v31, 64, v31
	s_add_i32 s12, s12, 2
	s_waitcnt lgkmcnt(9)
	v_mfma_f32_16x16x32_bf16 v[16:19], v[92:95], v[96:99], v[16:19]
	s_waitcnt lgkmcnt(8)
	v_mfma_f32_16x16x32_bf16 v[12:15], v[92:95], v[100:103], v[12:15]
	s_waitcnt lgkmcnt(7)
	v_mfma_f32_16x16x32_bf16 v[8:11], v[92:95], v[104:107], v[8:11]
	s_waitcnt lgkmcnt(6)
	v_mfma_f32_16x16x32_bf16 v[4:7], v[92:95], v[108:111], v[4:7]
	s_cmp_gt_i32 s12, s19
	s_cbranch_scc1 .Lhy_lat0_last_b
	ds_read2_b32 v[92:93], v30 offset1:1
	ds_read2_b32 v[94:95], v30 offset0:2 offset1:3
	ds_read_b128 v[96:99], v31
	ds_read_b128 v[100:103], v31 offset:5120
	ds_read_b128 v[104:107], v31 offset:10240
	ds_read_b128 v[108:111], v31 offset:15360
	v_subrev_u32_e32 v30, 64, v30
	v_subrev_u32_e32 v31, 64, v31
	s_add_i32 s12, s12, 2
	s_waitcnt lgkmcnt(9)
	v_mfma_f32_16x16x32_bf16 v[16:19], v[112:115], v[116:119], v[16:19]
	s_waitcnt lgkmcnt(8)
	v_mfma_f32_16x16x32_bf16 v[12:15], v[112:115], v[120:123], v[12:15]
	s_waitcnt lgkmcnt(7)
	v_mfma_f32_16x16x32_bf16 v[8:11], v[112:115], v[124:127], v[8:11]
	s_waitcnt lgkmcnt(6)
	v_mfma_f32_16x16x32_bf16 v[4:7], v[112:115], v[132:135], v[4:7]
	s_branch .Lhy_lat0_a
.Lhy_lat0_last_a:
	s_waitcnt lgkmcnt(3)
	v_mfma_f32_16x16x32_bf16 v[16:19], v[92:95], v[96:99], v[16:19]
	s_waitcnt lgkmcnt(2)
	v_mfma_f32_16x16x32_bf16 v[12:15], v[92:95], v[100:103], v[12:15]
	s_waitcnt lgkmcnt(1)
	v_mfma_f32_16x16x32_bf16 v[8:11], v[92:95], v[104:107], v[8:11]
	s_waitcnt lgkmcnt(0)
	v_mfma_f32_16x16x32_bf16 v[4:7], v[92:95], v[108:111], v[4:7]
	s_branch .Lhy_lat0_done
.Lhy_lat0_last_b:
	s_waitcnt lgkmcnt(3)
	v_mfma_f32_16x16x32_bf16 v[16:19], v[112:115], v[116:119], v[16:19]
	s_waitcnt lgkmcnt(2)
	v_mfma_f32_16x16x32_bf16 v[12:15], v[112:115], v[120:123], v[12:15]
	s_waitcnt lgkmcnt(1)
	v_mfma_f32_16x16x32_bf16 v[8:11], v[112:115], v[124:127], v[8:11]
	s_waitcnt lgkmcnt(0)
	v_mfma_f32_16x16x32_bf16 v[4:7], v[112:115], v[132:135], v[4:7]
.Lhy_lat0_done:
.LBB0_1266:
	s_xor_b64 s[12:13], s[6:7], -1
	s_and_b64 s[16:17], s[6:7], exec
	s_cselect_b32 s16, s82, 0xddf2000
	s_add_u32 s16, s8, s16
	s_addc_u32 s17, s9, 0
	v_cndmask_b32_e64 v30, v35, v34, s[6:7]
	s_and_b64 s[6:7], s[6:7], exec
	s_mov_b32 s6, 0x9380
	s_cselect_b32 s6, 0x4380, s6
	v_lshl_add_u64 v[32:33], v[20:21], 1, s[16:17]
	v_lshl_add_u32 v31, v20, 1, s6
	s_movk_i32 s6, 0x2000
	v_add_co_u32_e32 v42, vcc, s6, v32
	ds_read_b64 v[40:41], v31
	s_nop 0
	v_addc_co_u32_e32 v43, vcc, 0, v33, vcc
	flat_load_dwordx2 v[42:43], v[42:43]
	v_mov_b32_e32 v49, v18
	s_waitcnt lgkmcnt(0)
	v_lshlrev_b32_e32 v47, 16, v41
	v_lshlrev_b32_e32 v46, 16, v40
	v_and_b32_e32 v41, 0xffff0000, v41
	v_and_b32_e32 v40, 0xffff0000, v40
	v_mov_b32_e32 v18, v17
	v_mov_b32_e32 v48, v16
	v_pk_fma_f32 v[16:17], v[30:31], v[40:41], v[18:19] op_sel_hi:[0,1,1]
	v_pk_fma_f32 v[46:47], v[30:31], v[46:47], v[48:49] op_sel_hi:[0,1,1]
	s_mov_b64 s[6:7], -1
	s_and_b64 vcc, exec, s[12:13]
	s_waitcnt vmcnt(0)
	v_lshlrev_b32_e32 v45, 16, v43
	v_lshlrev_b32_e32 v44, 16, v42
	v_and_b32_e32 v43, 0xffff0000, v43
	v_and_b32_e32 v42, 0xffff0000, v42
	v_pk_mul_f32 v[16:17], v[16:17], v[42:43]
	v_pk_mul_f32 v[44:45], v[46:47], v[44:45]
	v_and_b32_sdwa v31, v17, v177 dst_sel:DWORD dst_unused:UNUSED_PAD src0_sel:WORD_1 src1_sel:DWORD
	v_and_b32_sdwa v40, v16, v177 dst_sel:DWORD dst_unused:UNUSED_PAD src0_sel:WORD_1 src1_sel:DWORD
	v_and_b32_sdwa v18, v45, v177 dst_sel:DWORD dst_unused:UNUSED_PAD src0_sel:WORD_1 src1_sel:DWORD
	v_and_b32_sdwa v19, v44, v177 dst_sel:DWORD dst_unused:UNUSED_PAD src0_sel:WORD_1 src1_sel:DWORD
	v_add3_u32 v17, v17, v31, s60
	v_add3_u32 v16, v16, v40, s60
	v_add3_u32 v19, v44, v19, s60
	v_add3_u32 v18, v45, v18, s60
	v_and_b32_e32 v17, 0xffff0000, v17
	v_and_b32_e32 v16, 0xffff0000, v16
	v_or_b32_sdwa v17, v17, v18 dst_sel:DWORD dst_unused:UNUSED_PAD src0_sel:DWORD src1_sel:WORD_1
	v_or_b32_sdwa v16, v16, v19 dst_sel:DWORD dst_unused:UNUSED_PAD src0_sel:DWORD src1_sel:WORD_1
	s_cbranch_vccz .LBB0_1268
	flat_store_dwordx2 v[22:23], v[16:17]
	s_mov_b64 s[6:7], 0

.LBB0_1336:
	ds_read2_b32 v[92:93], v18 offset1:1
	ds_read2_b32 v[94:95], v18 offset0:2 offset1:3
	ds_read_b128 v[96:99], v20
	ds_read_b128 v[100:103], v19
	v_subrev_u32_e32 v18, 64, v18
	v_subrev_u32_e32 v20, 64, v20
	v_subrev_u32_e32 v19, 64, v19
	s_add_i32 s17, s17, 2
.Lhy_ctx0_a:
	s_cmp_gt_i32 s17, 6
	s_cbranch_scc1 .Lhy_ctx0_last_a
	ds_read2_b32 v[112:113], v18 offset1:1
	ds_read2_b32 v[114:115], v18 offset0:2 offset1:3
	ds_read_b128 v[116:119], v20
	ds_read_b128 v[120:123], v19
	v_subrev_u32_e32 v18, 64, v18
	v_subrev_u32_e32 v20, 64, v20
	v_subrev_u32_e32 v19, 64, v19
	s_add_i32 s17, s17, 2
	s_waitcnt lgkmcnt(5)
	v_mfma_f32_16x16x32_bf16 v[8:11], v[92:95], v[96:99], v[8:11]
	s_waitcnt lgkmcnt(4)
	v_mfma_f32_16x16x32_bf16 v[4:7], v[92:95], v[100:103], v[4:7]
	s_cmp_gt_i32 s17, 6
	s_cbranch_scc1 .Lhy_ctx0_last_b
	ds_read2_b32 v[92:93], v18 offset1:1
	ds_read2_b32 v[94:95], v18 offset0:2 offset1:3
	ds_read_b128 v[96:99], v20
	ds_read_b128 v[100:103], v19
	v_subrev_u32_e32 v18, 64, v18
	v_subrev_u32_e32 v20, 64, v20
	v_subrev_u32_e32 v19, 64, v19
	s_add_i32 s17, s17, 2
	s_waitcnt lgkmcnt(5)
	v_mfma_f32_16x16x32_bf16 v[8:11], v[112:115], v[116:119], v[8:11]
	s_waitcnt lgkmcnt(4)
	v_mfma_f32_16x16x32_bf16 v[4:7], v[112:115], v[120:123], v[4:7]
	s_branch .Lhy_ctx0_a
.Lhy_ctx0_last_a:
	s_waitcnt lgkmcnt(1)
	v_mfma_f32_16x16x32_bf16 v[8:11], v[92:95], v[96:99], v[8:11]
	s_waitcnt lgkmcnt(0)
	v_mfma_f32_16x16x32_bf16 v[4:7], v[92:95], v[100:103], v[4:7]
	s_branch .Lhy_ctx0_done
.Lhy_ctx0_last_b:
	s_waitcnt lgkmcnt(1)
	v_mfma_f32_16x16x32_bf16 v[8:11], v[112:115], v[116:119], v[8:11]
	s_waitcnt lgkmcnt(0)
	v_mfma_f32_16x16x32_bf16 v[4:7], v[112:115], v[120:123], v[4:7]
.Lhy_ctx0_done:
	s_and_b64 s[18:19], s[6:7], exec
	s_cselect_b32 s44, s82, 0xddf2000
	v_lshl_add_u64 v[20:21], v[12:13], 0, s[44:45]
	v_lshl_add_u64 v[18:19], s[8:9], 1, v[20:21]
	flat_load_dwordx2 v[32:33], v[18:19]
	v_cndmask_b32_e64 v18, v23, v22, s[6:7]
	s_lshl_b32 s6, s14, 1
	s_add_i32 s6, s16, s6
	v_mov_b32_e32 v34, v8
	v_lshl_add_u32 v8, v25, 1, s6
	ds_read_b64 v[36:37], v8 offset:512
	v_mov_b32_e32 v35, v10
	v_mov_b32_e32 v10, v9
	s_mov_b64 s[6:7], -1
	s_and_b64 vcc, exec, s[12:13]
	s_waitcnt lgkmcnt(0)
	v_lshlrev_b32_e32 v9, 16, v37
	v_lshlrev_b32_e32 v8, 16, v36
	v_and_b32_e32 v37, 0xffff0000, v37
	v_and_b32_e32 v36, 0xffff0000, v36
	v_pk_fma_f32 v[8:9], v[18:19], v[8:9], v[34:35] op_sel_hi:[0,1,1]
	v_pk_fma_f32 v[10:11], v[18:19], v[36:37], v[10:11] op_sel_hi:[0,1,1]
	s_waitcnt vmcnt(0)
	v_lshlrev_b32_e32 v35, 16, v33
	v_lshlrev_b32_e32 v34, 16, v32
	v_and_b32_e32 v33, 0xffff0000, v33
	v_and_b32_e32 v32, 0xffff0000, v32
	v_pk_mul_f32 v[10:11], v[10:11], v[32:33]
	v_pk_mul_f32 v[8:9], v[8:9], v[34:35]
	v_and_b32_sdwa v32, v11, v177 dst_sel:DWORD dst_unused:UNUSED_PAD src0_sel:WORD_1 src1_sel:DWORD
	v_and_b32_sdwa v33, v10, v177 dst_sel:DWORD dst_unused:UNUSED_PAD src0_sel:WORD_1 src1_sel:DWORD
	v_and_b32_sdwa v19, v9, v177 dst_sel:DWORD dst_unused:UNUSED_PAD src0_sel:WORD_1 src1_sel:DWORD
	v_and_b32_sdwa v31, v8, v177 dst_sel:DWORD dst_unused:UNUSED_PAD src0_sel:WORD_1 src1_sel:DWORD
	v_add3_u32 v11, v11, v32, s60
	v_add3_u32 v10, v10, v33, s60
	v_add3_u32 v8, v8, v31, s60
	v_add3_u32 v9, v9, v19, s60
	v_and_b32_e32 v11, 0xffff0000, v11
	v_and_b32_e32 v10, 0xffff0000, v10
	v_or_b32_sdwa v9, v11, v9 dst_sel:DWORD dst_unused:UNUSED_PAD src0_sel:DWORD src1_sel:WORD_1
	v_or_b32_sdwa v8, v10, v8 dst_sel:DWORD dst_unused:UNUSED_PAD src0_sel:DWORD src1_sel:WORD_1
	s_cbranch_vccz .LBB0_1339
	flat_store_dwordx2 v[14:15], v[8:9]
	s_mov_b64 s[6:7], 0

.LBB0_3004:
	s_or_b64 exec, exec, s[6:7]
	s_sub_i32 s8, s10, 32
	s_ashr_i32 s9, s8, 31
	s_lshl_b64 s[6:7], s[8:9], 12
	v_readlane_b32 s20, v252, 15
	v_readlane_b32 s21, v252, 16
	s_add_u32 s16, s20, s6
	s_addc_u32 s17, s21, s7
	s_add_u32 s18, s16, 0x100000
	s_addc_u32 s19, s17, 0
	s_mul_i32 s7, s8, 0x6000
	s_mul_hi_i32 s6, s8, 0x6000
	s_add_u32 s8, s42, s7
	s_addc_u32 s9, s43, s6
	s_add_u32 s12, s8, 0xd1f4000
	s_addc_u32 s13, s9, 0
	s_movk_i32 s11, 0x7ff
	s_movk_i32 s20, 0x800
	v_sub_u32_e32 v10, 0x81f, v8
	v_add_u32_e32 v11, -1, v10
	v_add_u32_e32 v12, 0xfffffe00, v10
	v_add_u32_e32 v13, -1, v12
	v_add_u32_e32 v14, 0xfffffe00, v12
	v_add_u32_e32 v15, -1, v14
	v_add_u32_e32 v16, 0xfffffe00, v14
	v_add_u32_e32 v17, -1, v16
	v_add_u32_e32 v18, 0xfffffe00, v16
	v_add_u32_e32 v19, -1, v18
	v_med3_i32 v20, v10, 0, s11
	v_med3_i32 v21, v11, 0, s11
	v_med3_i32 v22, v12, 0, s11
	v_med3_i32 v23, v13, 0, s11
	v_med3_i32 v24, v14, 0, s11
	v_med3_i32 v25, v15, 0, s11
	v_med3_i32 v26, v16, 0, s11
	v_med3_i32 v27, v17, 0, s11
	v_med3_i32 v28, v18, 0, s11
	v_med3_i32 v29, v19, 0, s11
	v_lshlrev_b32_e32 v20, 1, v20
	v_lshlrev_b32_e32 v21, 1, v21
	v_lshlrev_b32_e32 v22, 1, v22
	v_lshlrev_b32_e32 v23, 1, v23
	v_lshlrev_b32_e32 v24, 1, v24
	v_lshlrev_b32_e32 v25, 1, v25
	v_lshlrev_b32_e32 v26, 1, v26
	v_lshlrev_b32_e32 v27, 1, v27
	v_lshlrev_b32_e32 v28, 1, v28
	v_lshlrev_b32_e32 v29, 1, v29
	global_load_ushort v30, v20, s[16:17]
	global_load_ushort v31, v21, s[16:17]
	global_load_ushort v32, v20, s[18:19]
	global_load_ushort v33, v21, s[18:19]
	global_load_ushort v34, v22, s[16:17]
	global_load_ushort v35, v23, s[16:17]
	global_load_ushort v36, v22, s[18:19]
	global_load_ushort v37, v23, s[18:19]
	global_load_ushort v38, v24, s[16:17]
	global_load_ushort v39, v25, s[16:17]
	global_load_ushort v40, v24, s[18:19]
	global_load_ushort v41, v25, s[18:19]
	global_load_ushort v42, v26, s[16:17]
	global_load_ushort v43, v27, s[16:17]
	global_load_ushort v44, v26, s[18:19]
	global_load_ushort v45, v27, s[18:19]
	global_load_ushort v46, v28, s[16:17]
	global_load_ushort v47, v29, s[16:17]
	global_load_ushort v48, v28, s[18:19]
	global_load_ushort v49, v29, s[18:19]
	v_lshrrev_b32_e32 v4, 8, v8
	v_and_b32_e32 v5, 0xff, v8
	v_lshlrev_b32_e32 v6, 12, v4
	v_lshl_add_u32 v6, v5, 4, v6
	v_add_u32_e32 v7, 0x2000, v6
	global_load_dwordx4 v[70:73], v6, s[12:13]
	global_load_dwordx4 v[74:77], v7, s[12:13]
	v_lshl_add_u32 v50, v8, 4, v179
	v_lshl_add_u32 v50, v4, 10, v50
	v_lshlrev_b32_e32 v51, 1, v8
	s_waitcnt vmcnt(2)
	v_cmp_gt_u32_e32 vcc, 0x800, v10
	v_cmp_gt_u32_e64 s[6:7], s20, v11
	s_nop 1
	v_cndmask_b32_e32 v30, 0, v30, vcc
	v_cndmask_b32_e32 v32, 0, v32, vcc
	v_cndmask_b32_e64 v31, 0, v31, s[6:7]
	v_cndmask_b32_e64 v33, 0, v33, s[6:7]
	ds_write_b16 v51, v30
	ds_write_b16 v51, v31 offset:4192
	ds_write_b16 v51, v32 offset:8384
	ds_write_b16 v51, v33 offset:12576
	v_cmp_gt_u32_e32 vcc, 0x800, v12
	v_cmp_gt_u32_e64 s[6:7], s20, v13
	s_nop 1
	v_cndmask_b32_e32 v34, 0, v34, vcc
	v_cndmask_b32_e32 v36, 0, v36, vcc
	v_cndmask_b32_e64 v35, 0, v35, s[6:7]
	v_cndmask_b32_e64 v37, 0, v37, s[6:7]
	ds_write_b16 v51, v34 offset:1024
	ds_write_b16 v51, v35 offset:5216
	ds_write_b16 v51, v36 offset:9408
	ds_write_b16 v51, v37 offset:13600
	v_cmp_gt_u32_e32 vcc, 0x800, v14
	v_cmp_gt_u32_e64 s[6:7], s20, v15
	s_nop 1
	v_cndmask_b32_e32 v38, 0, v38, vcc
	v_cndmask_b32_e32 v40, 0, v40, vcc
	v_cndmask_b32_e64 v39, 0, v39, s[6:7]
	v_cndmask_b32_e64 v41, 0, v41, s[6:7]
	ds_write_b16 v51, v38 offset:2048
	ds_write_b16 v51, v39 offset:6240
	ds_write_b16 v51, v40 offset:10432
	ds_write_b16 v51, v41 offset:14624
	v_cmp_gt_u32_e32 vcc, 0x800, v16
	v_cmp_gt_u32_e64 s[6:7], s20, v17
	s_nop 1
	v_cndmask_b32_e32 v42, 0, v42, vcc
	v_cndmask_b32_e32 v44, 0, v44, vcc
	v_cndmask_b32_e64 v43, 0, v43, s[6:7]
	v_cndmask_b32_e64 v45, 0, v45, s[6:7]
	ds_write_b16 v51, v42 offset:3072
	ds_write_b16 v51, v43 offset:7264
	ds_write_b16 v51, v44 offset:11456
	ds_write_b16 v51, v45 offset:15648
	v_cmp_gt_u32_e32 vcc, 48, v8
	s_and_saveexec_b64 s[22:23], vcc
	v_cmp_gt_u32_e32 vcc, 0x800, v18
	v_cmp_gt_u32_e64 s[6:7], s20, v19
	s_nop 1
	v_cndmask_b32_e32 v46, 0, v46, vcc
	v_cndmask_b32_e32 v48, 0, v48, vcc
	v_cndmask_b32_e64 v47, 0, v47, s[6:7]
	v_cndmask_b32_e64 v49, 0, v49, s[6:7]
	ds_write_b16 v51, v46 offset:4096
	ds_write_b16 v51, v47 offset:8288
	ds_write_b16 v51, v48 offset:12480
	ds_write_b16 v51, v49 offset:16672
	s_or_b64 exec, exec, s[22:23]
	s_waitcnt lgkmcnt(0)
	s_barrier
	s_waitcnt vmcnt(0)
	ds_write_b128 v50, v[70:73]
	ds_write_b128 v50, v[74:77] offset:10240
	s_mov_b64 s[6:7], exec

.Lhy_lat1_a:
	s_cmp_gt_i32 s12, s17
	s_cbranch_scc1 .Lhy_lat1_last_a
	ds_read2_b32 v[112:113], v30 offset1:1
	ds_read2_b32 v[114:115], v30 offset0:2 offset1:3
	ds_read_b128 v[116:119], v31
	ds_read_b128 v[120:123], v31 offset:5120
	ds_read_b128 v[124:127], v31 offset:10240
	ds_read_b128 v[132:135], v31 offset:15360
	v_subrev_u32_e32 v30, 64, v30
	v_subrev_u32_e32 v31, 64, v31
	s_add_i32 s12, s12, 2
	s_waitcnt lgkmcnt(9)
	v_mfma_f32_16x16x32_bf16 v[16:19], v[92:95], v[96:99], v[16:19]
	s_waitcnt lgkmcnt(8)
	v_mfma_f32_16x16x32_bf16 v[12:15], v[92:95], v[100:103], v[12:15]
	s_waitcnt lgkmcnt(7)
	v_mfma_f32_16x16x32_bf16 v[8:11], v[92:95], v[104:107], v[8:11]
	s_waitcnt lgkmcnt(6)
	v_mfma_f32_16x16x32_bf16 v[4:7], v[92:95], v[108:111], v[4:7]
	s_cmp_gt_i32 s12, s17
	s_cbranch_scc1 .Lhy_lat1_last_b
	ds_read2_b32 v[92:93], v30 offset1:1
	ds_read2_b32 v[94:95], v30 offset0:2 offset1:3
	ds_read_b128 v[96:99], v31
	ds_read_b128 v[100:103], v31 offset:5120
	ds_read_b128 v[104:107], v31 offset:10240
	ds_read_b128 v[108:111], v31 offset:15360
	v_subrev_u32_e32 v30, 64, v30
	v_subrev_u32_e32 v31, 64, v31
	s_add_i32 s12, s12, 2
	s_waitcnt lgkmcnt(9)
	v_mfma_f32_16x16x32_bf16 v[16:19], v[112:115], v[116:119], v[16:19]
	s_waitcnt lgkmcnt(8)
	v_mfma_f32_16x16x32_bf16 v[12:15], v[112:115], v[120:123], v[12:15]
	s_waitcnt lgkmcnt(7)
	v_mfma_f32_16x16x32_bf16 v[8:11], v[112:115], v[124:127], v[8:11]
	s_waitcnt lgkmcnt(6)
	v_mfma_f32_16x16x32_bf16 v[4:7], v[112:115], v[132:135], v[4:7]
	s_branch .Lhy_lat1_a

.Lhy_lat1_done:
.LBB0_3023:
	s_xor_b64 s[12:13], s[6:7], -1
	s_and_b64 s[18:19], s[6:7], exec
	s_cselect_b32 s18, s2, 0xddf2000
	s_add_u32 s18, s8, s18
	s_addc_u32 s19, s9, 0
	v_cndmask_b32_e64 v30, v35, v34, s[6:7]
	s_and_b64 s[6:7], s[6:7], exec
	s_mov_b32 s6, 0x9380
	s_cselect_b32 s6, 0x4380, s6
	v_lshl_add_u64 v[32:33], v[20:21], 1, s[18:19]
	v_lshl_add_u32 v31, v20, 1, s6
	s_movk_i32 s6, 0x2000
	v_add_co_u32_e32 v42, vcc, s6, v32
	ds_read_b64 v[40:41], v31
	s_nop 0
	v_addc_co_u32_e32 v43, vcc, 0, v33, vcc
	flat_load_dwordx2 v[42:43], v[42:43]
	v_mov_b32_e32 v49, v18
	s_waitcnt lgkmcnt(0)
	v_lshlrev_b32_e32 v47, 16, v41
	v_lshlrev_b32_e32 v46, 16, v40
	v_and_b32_e32 v41, 0xffff0000, v41
	v_and_b32_e32 v40, 0xffff0000, v40
	v_mov_b32_e32 v18, v17
	v_mov_b32_e32 v48, v16
	v_pk_fma_f32 v[16:17], v[30:31], v[40:41], v[18:19] op_sel_hi:[0,1,1]
	v_pk_fma_f32 v[46:47], v[30:31], v[46:47], v[48:49] op_sel_hi:[0,1,1]
	s_mov_b64 s[6:7], -1
	s_and_b64 vcc, exec, s[12:13]
	s_waitcnt vmcnt(0)
	v_lshlrev_b32_e32 v45, 16, v43
	v_lshlrev_b32_e32 v44, 16, v42
	v_and_b32_e32 v43, 0xffff0000, v43
	v_and_b32_e32 v42, 0xffff0000, v42
	v_pk_mul_f32 v[16:17], v[16:17], v[42:43]
	v_pk_mul_f32 v[44:45], v[46:47], v[44:45]
	v_and_b32_sdwa v31, v17, v176 dst_sel:DWORD dst_unused:UNUSED_PAD src0_sel:WORD_1 src1_sel:DWORD
	v_and_b32_sdwa v40, v16, v176 dst_sel:DWORD dst_unused:UNUSED_PAD src0_sel:WORD_1 src1_sel:DWORD
	v_and_b32_sdwa v18, v45, v176 dst_sel:DWORD dst_unused:UNUSED_PAD src0_sel:WORD_1 src1_sel:DWORD
	v_and_b32_sdwa v19, v44, v176 dst_sel:DWORD dst_unused:UNUSED_PAD src0_sel:WORD_1 src1_sel:DWORD
	v_add3_u32 v17, v17, v31, s93
	v_add3_u32 v16, v16, v40, s93
	v_add3_u32 v19, v44, v19, s93
	v_add3_u32 v18, v45, v18, s93
	v_and_b32_e32 v17, 0xffff0000, v17
	v_and_b32_e32 v16, 0xffff0000, v16
	v_or_b32_sdwa v17, v17, v18 dst_sel:DWORD dst_unused:UNUSED_PAD src0_sel:DWORD src1_sel:WORD_1
	v_or_b32_sdwa v16, v16, v19 dst_sel:DWORD dst_unused:UNUSED_PAD src0_sel:DWORD src1_sel:WORD_1
	s_cbranch_vccz .LBB0_3025
	flat_store_dwordx2 v[22:23], v[16:17]
	s_mov_b64 s[6:7], 0

.Lhy_ctx1_done:
	s_and_b64 s[18:19], s[6:7], exec
	s_cselect_b32 s44, s2, 0xddf2000
	v_lshl_add_u64 v[20:21], v[12:13], 0, s[44:45]
	v_lshl_add_u64 v[18:19], s[8:9], 1, v[20:21]
	flat_load_dwordx2 v[32:33], v[18:19]
	v_cndmask_b32_e64 v18, v23, v22, s[6:7]
	s_lshl_b32 s6, s14, 1
	s_add_i32 s6, s16, s6
	v_mov_b32_e32 v34, v8
	v_lshl_add_u32 v8, v25, 1, s6
	ds_read_b64 v[36:37], v8 offset:512
	v_mov_b32_e32 v35, v10
	v_mov_b32_e32 v10, v9
	s_mov_b64 s[6:7], -1
	s_and_b64 vcc, exec, s[12:13]
	s_waitcnt lgkmcnt(0)
	v_lshlrev_b32_e32 v9, 16, v37
	v_lshlrev_b32_e32 v8, 16, v36
	v_and_b32_e32 v37, 0xffff0000, v37
	v_and_b32_e32 v36, 0xffff0000, v36
	v_pk_fma_f32 v[8:9], v[18:19], v[8:9], v[34:35] op_sel_hi:[0,1,1]
	v_pk_fma_f32 v[10:11], v[18:19], v[36:37], v[10:11] op_sel_hi:[0,1,1]
	s_waitcnt vmcnt(0)
	v_lshlrev_b32_e32 v35, 16, v33
	v_lshlrev_b32_e32 v34, 16, v32
	v_and_b32_e32 v33, 0xffff0000, v33
	v_and_b32_e32 v32, 0xffff0000, v32
	v_pk_mul_f32 v[10:11], v[10:11], v[32:33]
	v_pk_mul_f32 v[8:9], v[8:9], v[34:35]
	v_and_b32_sdwa v32, v11, v176 dst_sel:DWORD dst_unused:UNUSED_PAD src0_sel:WORD_1 src1_sel:DWORD
	v_and_b32_sdwa v33, v10, v176 dst_sel:DWORD dst_unused:UNUSED_PAD src0_sel:WORD_1 src1_sel:DWORD
	v_and_b32_sdwa v19, v9, v176 dst_sel:DWORD dst_unused:UNUSED_PAD src0_sel:WORD_1 src1_sel:DWORD
	v_and_b32_sdwa v31, v8, v176 dst_sel:DWORD dst_unused:UNUSED_PAD src0_sel:WORD_1 src1_sel:DWORD
	v_add3_u32 v11, v11, v32, s93
	v_add3_u32 v10, v10, v33, s93
	v_add3_u32 v8, v8, v31, s93
	v_add3_u32 v9, v9, v19, s93
	v_and_b32_e32 v11, 0xffff0000, v11
	v_and_b32_e32 v10, 0xffff0000, v10
	v_or_b32_sdwa v9, v11, v9 dst_sel:DWORD dst_unused:UNUSED_PAD src0_sel:DWORD src1_sel:WORD_1
	v_or_b32_sdwa v8, v10, v8 dst_sel:DWORD dst_unused:UNUSED_PAD src0_sel:DWORD src1_sel:WORD_1
	s_cbranch_vccz .LBB0_3096
	flat_store_dwordx2 v[14:15], v[8:9]
	s_mov_b64 s[6:7], 0
